# pair8f plus one s_barrier per P0 weight item and one before the fp6 weight line stores: the eight waves of a CU convert and store in step
# speedup vs baseline: 1.0055x; 1.0004x over previous
; #define LAS __attribute__((address_space(3)))
; __device__ __forceinline__ void p0_transpose_item(const float* W, int K, int N, bf16_t* WT, LAS float* scr, int item, int lane) {
;     const int nblk = N / 32, kb = item / nblk, nb = item % nblk, k0 = 64 * kb, n0 = 32 * nb;
; #pragma unroll 8
;     for (int i = 0; i < 8; ++i) { const int kk = 8 * i + (lane >> 3), n4 = (lane & 7) * 4;
;         const f32x4 v4 = *(const f32x4*)(W + (size_t)(k0 + kk) * N + n0 + n4); LAS float* d4 = scr + kk * 33 + n4; d4[0] = v4[0]; d4[1] = v4[1]; d4[2] = v4[2]; d4[3] = v4[3]; }
;     LDS_WAIT(); asm volatile("" ::: "memory");
;     const int c = lane & 7;
; #pragma unroll
;     for (int j = 0; j < 4; ++j) { const int n = (lane >> 3) + 8 * j; const LAS float* s = scr + (8 * c) * 33 + n;
;         u32x4 o; o.x = pk2(s[0 * 33], s[1 * 33]); o.y = pk2(s[2 * 33], s[3 * 33]); o.z = pk2(s[4 * 33], s[5 * 33]); o.w = pk2(s[6 * 33], s[7 * 33]);
;         *(u32x4*)(WT + (size_t)(n0 + n) * K + k0 + 8 * c) = o; }
;     LDS_WAIT(); asm volatile("" ::: "memory");
; }
; __device__ __forceinline__ void p0_prologue(const Frame& F) {
;     ...
;     for (int it = gw; it < NITEMS; it += NGW) {
;         int r = it;
;         if (r < I_6) { const int kt = r / NB6, nb = r % NB6;
;             if (nb < 384) p0_transpose_pair_fp6(F.w_in, DM, NIN, 6144 + 32 * nb, F.WinT8, 32 * nb, scr, 2 * kt, plane);
;             else          p0_transpose_pair_fp6(F.w_in, DM, NIN, 24576 + 32 * (nb - 384), F.WinT8, 12288 + 32 * (nb - 384), scr, 2 * kt, plane);
;             continue; } r -= I_6;
;         if (r < I_IN) { const int kb = r / NBO, nb = r % NBO;
;             if (nb < 192) { const int n0 = 32 * nb;
;                 const int r0 = n0 < 2048 ? (n0 >> 7) * 256 + (n0 & 127) : (n0 < 4096 ? 4096 + (n0 - 2048) : ((n0 - 4096) >> 7) * 256 + 128 + ((n0 - 4096) & 127));
;                 p0_transpose_item_cols(F.w_in, DM, NIN, n0, F.WinT16, r0, scr, kb, plane); }
;             else if (nb < 384)  p0_transpose_item_fp4(F.w_in, DM, NIN, 18432 + 32 * (nb - 192), F.WinT4, 32 * (nb - 192), scr, kb, plane);
;             else                p0_transpose_item_fp4(F.w_in, DM, NIN, 30720 + 32 * (nb - 384), F.WinT4, 6144 + 32 * (nb - 384), scr, kb, plane);
;             continue; } r -= I_IN;
;         if (r < I_A) { p0_transpose_item(F.w_pa, EA, DM, F.WaT, scr, r, plane); continue; } r -= I_A;
.LBB0_15:
	s_barrier
	s_cmpk_gt_i32 s70, 0x47ff
	s_mov_b64 s[58:59], -1
	s_cbranch_scc0 .LBB0_44
	s_cmpk_gt_u32 s70, 0xc7ff
	s_cbranch_scc0 .LBB0_26
	s_cmpk_gt_u32 s70, 0xd7ff
	s_cbranch_scc0 .LBB0_23
	s_cmpk_gt_u32 s70, 0xe7ff
	s_cbranch_scc0 .LBB0_20
	s_add_i32 s0, s70, 0xffff1800
	s_lshr_b32 s0, s0, 1
	s_and_b32 s59, s0, 0xfc0
	s_add_i32 s0, s10, 0xffe30000
	s_and_b32 s58, s0, 0xfe0
	s_lshl_b32 s0, s58, 2
	v_or_b32_e32 v0, s59, v64
	v_lshl_add_u64 v[28:29], v[38:39], 0, s[0:1]
	v_lshlrev_b32_e32 v32, 14, v0
	v_or_b32_e32 v2, s59, v65
	v_lshl_add_u64 v[0:1], v[28:29], 0, v[32:33]
	v_lshlrev_b32_e32 v32, 14, v2
	v_or_b32_e32 v8, s59, v67
	v_lshl_add_u64 v[4:5], v[28:29], 0, v[32:33]
	v_lshlrev_b32_e32 v32, 14, v8
	v_or_b32_e32 v10, s59, v69
	v_lshl_add_u64 v[8:9], v[28:29], 0, v[32:33]
	v_lshlrev_b32_e32 v32, 14, v10
	v_or_b32_e32 v16, s59, v70
	v_lshl_add_u64 v[12:13], v[28:29], 0, v[32:33]
	v_lshlrev_b32_e32 v32, 14, v16
	v_or_b32_e32 v18, s59, v71
	v_lshl_add_u64 v[16:17], v[28:29], 0, v[32:33]
	v_lshlrev_b32_e32 v32, 14, v18
	v_lshl_add_u64 v[20:21], v[28:29], 0, v[32:33]
	global_load_dwordx4 v[0:3], v[0:1], off
	s_nop 0
	global_load_dwordx4 v[4:7], v[4:5], off
	s_nop 0
	global_load_dwordx4 v[8:11], v[8:9], off
	s_nop 0
	global_load_dwordx4 v[12:15], v[12:13], off
	s_nop 0
	global_load_dwordx4 v[16:19], v[16:17], off
	s_nop 0
	global_load_dwordx4 v[20:23], v[20:21], off
	v_or_b32_e32 v24, s59, v72
	v_lshlrev_b32_e32 v32, 14, v24
	v_lshl_add_u64 v[24:25], v[28:29], 0, v[32:33]
	v_or_b32_e32 v30, s59, v73
	global_load_dwordx4 v[24:27], v[24:25], off
	v_lshlrev_b32_e32 v32, 14, v30
	v_lshl_add_u64 v[28:29], v[28:29], 0, v[32:33]
	global_load_dwordx4 v[28:31], v[28:29], off
	v_or_b32_e32 v32, s58, v64
	s_lshl_b32 s0, s59, 1
	v_or_b32_e32 v60, s58, v65
	v_lshl_add_u64 v[56:57], v[40:41], 0, s[0:1]
	v_lshlrev_b32_e32 v32, 13, v32
	v_or_b32_e32 v62, s58, v67
	v_lshl_add_u64 v[58:59], v[56:57], 0, v[32:33]
	v_lshlrev_b32_e32 v32, 13, v60
	v_lshl_add_u64 v[60:61], v[56:57], 0, v[32:33]
	v_lshlrev_b32_e32 v32, 13, v62
	v_lshl_add_u64 v[62:63], v[56:57], 0, v[32:33]
	s_waitcnt vmcnt(7)
	ds_write2_b32 v37, v0, v1 offset1:1
	ds_write2_b32 v37, v2, v3 offset0:2 offset1:3
	s_waitcnt vmcnt(6)
	ds_write2_b32 v79, v4, v5 offset1:1
	ds_write2_b32 v80, v6, v7 offset1:1
	s_waitcnt vmcnt(5)
	ds_write2_b32 v81, v8, v9 offset1:1
	ds_write2_b32 v82, v10, v11 offset1:1
	s_waitcnt vmcnt(4)
	ds_write2_b32 v83, v12, v13 offset1:1
	ds_write2_b32 v84, v14, v15 offset1:1
	s_waitcnt vmcnt(3)
	ds_write2_b32 v85, v16, v17 offset1:1
	ds_write2_b32 v86, v18, v19 offset1:1
	s_waitcnt vmcnt(2)
	ds_write2_b32 v87, v20, v21 offset1:1
	ds_write2_b32 v88, v22, v23 offset1:1
	s_waitcnt vmcnt(1)
	ds_write2_b32 v89, v24, v25 offset1:1
	ds_write2_b32 v90, v26, v27 offset1:1
	s_waitcnt vmcnt(0)
	ds_write2_b32 v91, v28, v29 offset1:1
	ds_write2_b32 v92, v30, v31 offset1:1
	s_waitcnt lgkmcnt(0)
	ds_read2_b32 v[4:5], v74 offset0:33 offset1:41
	ds_read2_b32 v[6:7], v74 offset1:8
	ds_read2_b32 v[8:9], v74 offset0:66 offset1:74
	ds_read2_b32 v[10:11], v74 offset0:99 offset1:107
	ds_read2_b32 v[12:13], v74 offset0:132 offset1:140
	ds_read2_b32 v[14:15], v74 offset0:165 offset1:173
	ds_read2_b32 v[16:17], v74 offset0:198 offset1:206
	ds_read2_b32 v[18:19], v74 offset0:231 offset1:239
	ds_read2_b32 v[20:21], v74 offset0:49 offset1:57
	ds_read2_b32 v[22:23], v74 offset0:16 offset1:24
	ds_read2_b32 v[24:25], v74 offset0:82 offset1:90
	ds_read2_b32 v[26:27], v74 offset0:115 offset1:123
	ds_read2_b32 v[28:29], v74 offset0:148 offset1:156
	ds_read2_b32 v[30:31], v74 offset0:181 offset1:189
	ds_read2_b32 v[96:97], v74 offset0:214 offset1:222
	ds_read2_b32 v[98:99], v74 offset0:247 offset1:255
	s_waitcnt lgkmcnt(14)
	v_cvt_pk_bf16_f32 v0, v6, v4
	s_waitcnt lgkmcnt(12)
	v_cvt_pk_bf16_f32 v1, v8, v10
	s_waitcnt lgkmcnt(10)
	v_cvt_pk_bf16_f32 v2, v12, v14
	s_waitcnt lgkmcnt(8)
	v_cvt_pk_bf16_f32 v3, v16, v18
	v_cvt_pk_bf16_f32 v4, v7, v5
	v_cvt_pk_bf16_f32 v5, v9, v11
	v_cvt_pk_bf16_f32 v6, v13, v15
	v_cvt_pk_bf16_f32 v7, v17, v19
	s_waitcnt lgkmcnt(6)
	v_cvt_pk_bf16_f32 v8, v22, v20
	s_waitcnt lgkmcnt(4)
	v_cvt_pk_bf16_f32 v9, v24, v26
	s_waitcnt lgkmcnt(2)
	v_cvt_pk_bf16_f32 v10, v28, v30
	s_waitcnt lgkmcnt(0)
	v_cvt_pk_bf16_f32 v11, v96, v98
	global_store_dwordx4 v[58:59], v[0:3], off
	global_store_dwordx4 v[60:61], v[4:7], off
	global_store_dwordx4 v[62:63], v[8:11], off
	v_or_b32_e32 v0, s58, v69
	v_lshlrev_b32_e32 v32, 13, v0
	v_cvt_pk_bf16_f32 v12, v23, v21
	v_cvt_pk_bf16_f32 v13, v25, v27
	v_cvt_pk_bf16_f32 v14, v29, v31
	v_cvt_pk_bf16_f32 v15, v97, v99
	v_lshl_add_u64 v[0:1], v[56:57], 0, v[32:33]
	global_store_dwordx4 v[0:1], v[12:15], off
	s_waitcnt lgkmcnt(0)
	s_mov_b64 s[58:59], 0

; #define LAS __attribute__((address_space(3)))
; #define LDS_WAIT() asm volatile("s_waitcnt lgkmcnt(0)" ::: "memory")
;     __device__ __forceinline__ unsigned a(const pg8::Unit& u) const { return (unsigned)u.pm * (256u * K * 2u); }
;     __device__ __forceinline__ unsigned a(const pg8::Unit& u) const { return (unsigned)u.pm * (256u * K * 2u); }
;     __device__ __forceinline__ unsigned a(const pg8::Unit& u) const { return (unsigned)u.pm * (256u * K * 2u); }
;     __device__ __forceinline__ unsigned a(const pg8::Unit& u) const { return (unsigned)u.pm * (256u * K * 2u); }
;     __device__ __forceinline__ unsigned a(const pg8::Unit& u) const { return (unsigned)u.pm * (256u * K * 2u); }
; __device__ __forceinline__ void p0_transpose_pair_fp6(const float* W, int K, int N, int ncol0, unsigned char* WT6, int row0, LAS float* scr, int kb, int lane) {
;     LAS unsigned* stg = (LAS unsigned*)(scr + 64 * 33);
;     const int n = lane & 31, grp = lane >> 5;
; #pragma unroll
;     for (int h = 0; h < 2; ++h) {
;         const int k0 = 64 * (kb + h);
; #pragma unroll 8
;         for (int i = 0; i < 8; ++i) { const int kk = 8 * i + (lane >> 3), n4 = (lane & 7) * 4;
;         const f32x4 v4 = *(const f32x4*)(W + (size_t)(k0 + kk) * N + ncol0 + n4); LAS float* d4 = scr + kk * 33 + n4; d4[0] = v4[0]; d4[1] = v4[1]; d4[2] = v4[2]; d4[3] = v4[3]; }
;         LDS_WAIT(); asm volatile("" ::: "memory");
;         f32x16v a, b;
; #pragma unroll
;         for (int i = 0; i < 16; ++i) { a[i] = __builtin_amdgcn_fmed3f(scr[(grp * 32 + i) * 33 + n] * W6_SCALE, -7.5f, 7.5f); b[i] = __builtin_amdgcn_fmed3f(scr[(grp * 32 + 16 + i) * 33 + n] * W6_SCALE, -7.5f, 7.5f); }
; __device__ __forceinline__ void p0_prologue(const Frame& F) {
;     ...
;         if (r < I_6) { const int kt = r / NB6, nb = r % NB6;
;             if (nb < 384) p0_transpose_pair_fp6(F.w_in, DM, NIN, 6144 + 32 * nb, F.WinT8, 32 * nb, scr, 2 * kt, plane);
;             else          p0_transpose_pair_fp6(F.w_in, DM, NIN, 24576 + 32 * (nb - 384), F.WinT8, 12288 + 32 * (nb - 384), scr, 2 * kt, plane);
.LBB0_44:
	s_andn2_b64 vcc, exec, s[58:59]
	s_cbranch_vccnz .LBB0_14
	s_mul_hi_i32 s0, s70, 0x38e38e39
	s_lshr_b32 s58, s0, 31
	s_ashr_i32 s0, s0, 7
	s_add_i32 s0, s0, s58
	s_mul_i32 s58, s0, 0xfffffdc0
	s_add_i32 s59, s70, s58
	s_mul_i32 s58, s0, 0xffffb800
	s_add_i32 s62, s10, s58
	s_lshl_b32 s58, s0, 7
	v_or_b32_e32 v0, s58, v64
	v_mad_i64_i32 v[60:61], s[66:67], v0, s68, 0
	v_or_b32_e32 v0, s58, v65
	v_mad_i64_i32 v[58:59], s[66:67], v0, s68, 0
	s_cmpk_gt_i32 s59, 0x17f
	s_mov_b64 s[66:67], -1
	v_or_b32_e32 v104, s58, v67
	v_or_b32_e32 v103, s58, v69
	v_or_b32_e32 v102, s58, v70
	v_or_b32_e32 v101, s58, v71
	v_or_b32_e32 v100, s58, v72
	v_or_b32_e32 v99, s58, v73
	v_lshlrev_b32_e32 v32, 2, v34
	v_add_u32_e32 v98, 0x800, v75
	v_add_u32_e32 v97, 0x400, v75
	v_add_u32_e32 v96, 0xc00, v75
	v_add_u32_e32 v95, v77, v78
	v_lshrrev_b32_e32 v124, 1, v66
	v_and_b32_e32 v124, v124, v66
	v_bfe_u32 v124, v124, 1, 1
	v_lshlrev_b32_e32 v125, 5, v124
	v_sub_u32_e32 v124, v95, v125
	v_add_u32_e32 v56, s62, v64
	s_cbranch_scc0 .LBB0_47
	s_mov_b32 s63, s1
	s_lshl_b64 s[66:67], s[62:63], 2
	s_add_u32 s66, s16, s66
	s_addc_u32 s67, s17, s67
	v_lshl_add_u64 v[0:1], s[66:67], 0, v[32:33]
	v_lshl_add_u64 v[62:63], v[0:1], 0, s[6:7]
	v_lshl_add_u64 v[0:1], v[62:63], 0, v[60:61]
	v_lshl_add_u64 v[4:5], v[62:63], 0, v[58:59]
	v_mad_i64_i32 v[8:9], s[66:67], v104, s68, v[62:63]
	v_mad_i64_i32 v[12:13], s[66:67], v103, s68, v[62:63]
	v_mad_i64_i32 v[16:17], s[66:67], v102, s68, v[62:63]
	v_mad_i64_i32 v[20:21], s[66:67], v101, s68, v[62:63]
	global_load_dwordx4 v[0:3], v[0:1], off
	s_nop 0
	global_load_dwordx4 v[4:7], v[4:5], off
	s_nop 0
	global_load_dwordx4 v[8:11], v[8:9], off
	s_nop 0
	global_load_dwordx4 v[12:15], v[12:13], off
	s_nop 0
	global_load_dwordx4 v[16:19], v[16:17], off
	s_nop 0
	global_load_dwordx4 v[20:23], v[20:21], off
	v_mad_i64_i32 v[24:25], s[66:67], v100, s68, v[62:63]
	global_load_dwordx4 v[24:27], v[24:25], off
	v_mad_i64_i32 v[28:29], s[66:67], v99, s68, v[62:63]
	global_load_dwordx4 v[28:31], v[28:29], off
	s_or_b32 s0, s58, 64
	s_ashr_i32 s59, s58, 31
	v_mov_b32_e32 v57, v33
	s_waitcnt vmcnt(7)
	ds_write2_b32 v37, v0, v1 offset1:1
	ds_write2_b32 v37, v2, v3 offset0:2 offset1:3
	s_waitcnt vmcnt(6)
	ds_write2_b32 v79, v4, v5 offset1:1
	ds_write2_b32 v80, v6, v7 offset1:1
	s_waitcnt vmcnt(5)
	ds_write2_b32 v81, v8, v9 offset1:1
	ds_write2_b32 v82, v10, v11 offset1:1
	s_waitcnt vmcnt(4)
	ds_write2_b32 v83, v12, v13 offset1:1
	ds_write2_b32 v84, v14, v15 offset1:1
	s_waitcnt vmcnt(3)
	ds_write2_b32 v85, v16, v17 offset1:1
	ds_write2_b32 v86, v18, v19 offset1:1
	s_waitcnt vmcnt(2)
	ds_write2_b32 v87, v20, v21 offset1:1
	ds_write2_b32 v88, v22, v23 offset1:1
	s_waitcnt vmcnt(1)
	ds_write2_b32 v89, v24, v25 offset1:1
	ds_write2_b32 v90, v26, v27 offset1:1
	s_waitcnt vmcnt(0)
	ds_write2_b32 v91, v28, v29 offset1:1
	ds_write2_b32 v92, v30, v31 offset1:1
	s_waitcnt lgkmcnt(0)
	ds_read2_b32 v[0:1], v75 offset1:33
	ds_read2_b32 v[2:3], v98 offset0:16 offset1:49
	ds_read2_b32 v[4:5], v75 offset0:66 offset1:99
	ds_read2_b32 v[6:7], v98 offset0:82 offset1:115
	ds_read2_b32 v[8:9], v75 offset0:132 offset1:165
	ds_read2_b32 v[10:11], v98 offset0:148 offset1:181
	ds_read2_b32 v[12:13], v75 offset0:198 offset1:231
	ds_read2_b32 v[14:15], v98 offset0:214 offset1:247
	ds_read2_b32 v[16:17], v97 offset0:8 offset1:41
	ds_read2_b32 v[18:19], v96 offset0:24 offset1:57
	ds_read2_b32 v[26:27], v97 offset0:74 offset1:107
	ds_read2_b32 v[28:29], v96 offset0:90 offset1:123
	s_waitcnt lgkmcnt(4)
	v_mul_f32_e32 v14, 0x43000000, v14
	v_mul_f32_e32 v15, 0x43000000, v15
	v_med3_f32 v22, v14, s69, v94
	v_med3_f32 v23, v15, s69, v94
	ds_read2_b32 v[14:15], v96 offset0:156 offset1:189
	v_mul_f32_e32 v2, 0x43000000, v2
	v_mul_f32_e32 v3, 0x43000000, v3
	v_mul_f32_e32 v4, 0x43000000, v4
	v_mul_f32_e32 v6, 0x43000000, v6
	v_mul_f32_e32 v5, 0x43000000, v5
	v_mul_f32_e32 v7, 0x43000000, v7
	v_mul_f32_e32 v8, 0x43000000, v8
	v_mul_f32_e32 v9, 0x43000000, v9
	v_mul_f32_e32 v12, 0x43000000, v12
	v_mul_f32_e32 v13, 0x43000000, v13
	s_waitcnt lgkmcnt(4)
	v_mul_f32_e32 v24, 0x43000000, v16
	s_waitcnt lgkmcnt(3)
	v_mul_f32_e32 v25, 0x43000000, v18
	v_mul_f32_e32 v30, 0x43000000, v17
	v_mul_f32_e32 v31, 0x43000000, v19
	ds_read2_b32 v[106:107], v96 offset0:222 offset1:255
	v_med3_f32 v16, v2, s69, v94
	v_med3_f32 v17, v3, s69, v94
	v_med3_f32 v2, v4, s69, v94
	v_med3_f32 v18, v6, s69, v94
	v_med3_f32 v3, v5, s69, v94
	v_med3_f32 v19, v7, s69, v94
	v_med3_f32 v4, v8, s69, v94
	v_med3_f32 v5, v9, s69, v94
	v_med3_f32 v6, v12, s69, v94
	v_med3_f32 v7, v13, s69, v94
	v_med3_f32 v8, v24, s69, v94
	v_med3_f32 v24, v25, s69, v94
	v_med3_f32 v9, v30, s69, v94
	v_med3_f32 v25, v31, s69, v94
	ds_read2_b32 v[12:13], v97 offset0:140 offset1:173
	ds_read2_b32 v[30:31], v97 offset0:206 offset1:239
	v_mul_f32_e32 v11, 0x43000000, v11
	s_waitcnt lgkmcnt(3)
	v_mul_f32_e32 v14, 0x43000000, v14
	v_mul_f32_e32 v10, 0x43000000, v10
	v_med3_f32 v21, v11, s69, v94
	v_mul_f32_e32 v11, 0x43000000, v28
	v_med3_f32 v28, v14, s69, v94
	v_mul_f32_e32 v14, 0x43000000, v15
	s_waitcnt lgkmcnt(2)
	v_mul_f32_e32 v15, 0x43000000, v106
	v_mul_f32_e32 v0, 0x43000000, v0
	v_mul_f32_e32 v1, 0x43000000, v1
	v_med3_f32 v20, v10, s69, v94
	v_mul_f32_e32 v10, 0x43000000, v26
	v_med3_f32 v26, v11, s69, v94
	v_mul_f32_e32 v11, 0x43000000, v27
	v_mul_f32_e32 v27, 0x43000000, v29
	s_waitcnt lgkmcnt(1)
	v_mul_f32_e32 v12, 0x43000000, v12
	v_mul_f32_e32 v13, 0x43000000, v13
	v_med3_f32 v29, v14, s69, v94
	s_waitcnt lgkmcnt(0)
; #define LAS __attribute__((address_space(3)))
; #define LDS_WAIT() asm volatile("s_waitcnt lgkmcnt(0)" ::: "memory")
;     __device__ __forceinline__ unsigned a(const pg8::Unit& u) const { return (unsigned)u.pm * (256u * K * 2u); }
;     __device__ __forceinline__ unsigned a(const pg8::Unit& u) const { return (unsigned)u.pm * (256u * K * 2u); }
;     __device__ __forceinline__ unsigned a(const pg8::Unit& u) const { return (unsigned)u.pm * (256u * K * 2u); }
;     __device__ __forceinline__ unsigned a(const pg8::Unit& u) const { return (unsigned)u.pm * (256u * K * 2u); }
;     __device__ __forceinline__ unsigned a(const pg8::Unit& u) const { return (unsigned)u.pm * (256u * K * 2u); }
; __device__ __forceinline__ void p0_transpose_pair_fp6(const float* W, int K, int N, int ncol0, unsigned char* WT6, int row0, LAS float* scr, int kb, int lane) {
;     ...
;         for (int i = 0; i < 8; ++i) { const int kk = 8 * i + (lane >> 3), n4 = (lane & 7) * 4;
;         const f32x4 v4 = *(const f32x4*)(W + (size_t)(k0 + kk) * N + ncol0 + n4); LAS float* d4 = scr + kk * 33 + n4; d4[0] = v4[0]; d4[1] = v4[1]; d4[2] = v4[2]; d4[3] = v4[3]; }
;         LDS_WAIT(); asm volatile("" ::: "memory");
;         f32x16v a, b;
; #pragma unroll
;         for (int i = 0; i < 16; ++i) { a[i] = __builtin_amdgcn_fmed3f(scr[(grp * 32 + i) * 33 + n] * W6_SCALE, -7.5f, 7.5f); b[i] = __builtin_amdgcn_fmed3f(scr[(grp * 32 + 16 + i) * 33 + n] * W6_SCALE, -7.5f, 7.5f); }
;         const u32x6v p = __builtin_amdgcn_cvt_scalef32_2xpk16_fp6_f32(a, b, 1.0f);
;         const int fq = h * 2 + grp;
;         *(LAS u32x4*)(stg + n * 36 + fq * 4) = (u32x4){p[0], p[1], p[2], p[3]};
;         *(LAS u32x4*)(stg + n * 36 + 16 + fq * 4) = (u32x4){p[4], p[5], 0u, 0u};
;         LDS_WAIT(); asm volatile("" ::: "memory");
	v_mul_f32_e32 v14, 0x43000000, v30
	v_med3_f32 v30, v15, s69, v94
	v_mul_f32_e32 v15, 0x43000000, v31
	v_mul_f32_e32 v31, 0x43000000, v107
	v_med3_f32 v0, v0, s69, v94
	v_med3_f32 v1, v1, s69, v94
	v_med3_f32 v10, v10, s69, v94
	v_med3_f32 v11, v11, s69, v94
	v_med3_f32 v27, v27, s69, v94
	v_med3_f32 v12, v12, s69, v94
	v_med3_f32 v13, v13, s69, v94
	v_med3_f32 v14, v14, s69, v94
	v_med3_f32 v15, v15, s69, v94
	v_med3_f32 v31, v31, s69, v94
	v_cvt_scalef32_2xpk16_fp6_f32 v[0:5], v[0:15], v[16:31], 1.0
	ds_write_b128 v120, v[0:3] offset:8448
	v_mov_b32_e32 v0, v4
	v_mov_b32_e32 v1, v5
	v_mov_b32_e32 v2, v33
	v_mov_b32_e32 v3, v33
	ds_write_b64 v122, v[0:1] offset:8512
	s_waitcnt lgkmcnt(0)
	v_or_b32_e32 v0, s0, v64
	v_or_b32_e32 v2, s0, v65
	v_or_b32_e32 v8, s0, v67
	v_or_b32_e32 v10, s0, v69
	v_or_b32_e32 v16, s0, v70
	v_or_b32_e32 v18, s0, v71
	v_mad_i64_i32 v[0:1], s[66:67], v0, s68, v[62:63]
	v_mad_i64_i32 v[4:5], s[66:67], v2, s68, v[62:63]
	v_mad_i64_i32 v[8:9], s[66:67], v8, s68, v[62:63]
	v_mad_i64_i32 v[12:13], s[66:67], v10, s68, v[62:63]
	v_mad_i64_i32 v[16:17], s[66:67], v16, s68, v[62:63]
	v_mad_i64_i32 v[20:21], s[66:67], v18, s68, v[62:63]
	global_load_dwordx4 v[0:3], v[0:1], off
	s_nop 0
	global_load_dwordx4 v[4:7], v[4:5], off
	s_nop 0
	global_load_dwordx4 v[8:11], v[8:9], off
	s_nop 0
	global_load_dwordx4 v[12:15], v[12:13], off
	s_nop 0
	global_load_dwordx4 v[16:19], v[16:17], off
	s_nop 0
	global_load_dwordx4 v[20:23], v[20:21], off
	v_or_b32_e32 v24, s0, v72
	v_mad_i64_i32 v[24:25], s[66:67], v24, s68, v[62:63]
	global_load_dwordx4 v[24:27], v[24:25], off
	v_or_b32_e32 v28, s0, v73
	v_mad_i64_i32 v[28:29], s[66:67], v28, s68, v[62:63]
	global_load_dwordx4 v[28:31], v[28:29], off
	s_waitcnt vmcnt(7)
	ds_write2_b32 v37, v0, v1 offset1:1
	ds_write2_b32 v37, v2, v3 offset0:2 offset1:3
	s_waitcnt vmcnt(6)
	ds_write2_b32 v79, v4, v5 offset1:1
	ds_write2_b32 v80, v6, v7 offset1:1
	s_waitcnt vmcnt(5)
	ds_write2_b32 v81, v8, v9 offset1:1
	ds_write2_b32 v82, v10, v11 offset1:1
	s_waitcnt vmcnt(4)
	ds_write2_b32 v83, v12, v13 offset1:1
	ds_write2_b32 v84, v14, v15 offset1:1
	s_waitcnt vmcnt(3)
	ds_write2_b32 v85, v16, v17 offset1:1
	ds_write2_b32 v86, v18, v19 offset1:1
	s_waitcnt vmcnt(2)
	ds_write2_b32 v87, v20, v21 offset1:1
	ds_write2_b32 v88, v22, v23 offset1:1
	s_waitcnt vmcnt(1)
	ds_write2_b32 v89, v24, v25 offset1:1
	ds_write2_b32 v90, v26, v27 offset1:1
	s_waitcnt vmcnt(0)
	ds_write2_b32 v91, v28, v29 offset1:1
	ds_write2_b32 v92, v30, v31 offset1:1
	s_waitcnt lgkmcnt(0)
	ds_read2_b32 v[0:1], v75 offset1:33
	ds_read2_b32 v[2:3], v98 offset0:16 offset1:49
	ds_read2_b32 v[6:7], v98 offset0:82 offset1:115
	ds_read2_b32 v[8:9], v98 offset0:148 offset1:181
	ds_read2_b32 v[10:11], v98 offset0:214 offset1:247
	ds_read2_b32 v[12:13], v96 offset0:24 offset1:57
	s_waitcnt lgkmcnt(4)
	v_mul_f32_e32 v2, 0x43000000, v2
	ds_read2_b32 v[14:15], v96 offset0:90 offset1:123
	v_med3_f32 v16, v2, s69, v94
	v_mul_f32_e32 v2, 0x43000000, v3
	s_waitcnt lgkmcnt(4)
	v_mul_f32_e32 v3, 0x43000000, v6
	v_mul_f32_e32 v6, 0x43000000, v7
	ds_read2_b32 v[28:29], v96 offset0:156 offset1:189
	ds_read2_b32 v[4:5], v75 offset0:66 offset1:99
	v_med3_f32 v19, v6, s69, v94
	s_waitcnt lgkmcnt(5)
	v_mul_f32_e32 v6, 0x43000000, v8
	v_mul_f32_e32 v8, 0x43000000, v9
	v_med3_f32 v21, v8, s69, v94
	s_waitcnt lgkmcnt(4)
	v_mul_f32_e32 v8, 0x43000000, v10
	v_mul_f32_e32 v10, 0x43000000, v11
	v_med3_f32 v23, v10, s69, v94
	s_waitcnt lgkmcnt(3)
	v_mul_f32_e32 v10, 0x43000000, v12
	v_mul_f32_e32 v12, 0x43000000, v13
	v_med3_f32 v25, v12, s69, v94
	s_waitcnt lgkmcnt(2)
	v_mul_f32_e32 v12, 0x43000000, v14
	v_mul_f32_e32 v14, 0x43000000, v15
	v_med3_f32 v27, v14, s69, v94
	s_waitcnt lgkmcnt(1)
	v_mul_f32_e32 v14, 0x43000000, v28
	v_med3_f32 v17, v2, s69, v94
	s_waitcnt lgkmcnt(0)
	v_mul_f32_e32 v2, 0x43000000, v4
	v_med3_f32 v18, v3, s69, v94
	v_mul_f32_e32 v3, 0x43000000, v5
	ds_read2_b32 v[4:5], v75 offset0:132 offset1:165
	v_med3_f32 v20, v6, s69, v94
	ds_read2_b32 v[6:7], v75 offset0:198 offset1:231
	v_med3_f32 v22, v8, s69, v94
	ds_read2_b32 v[8:9], v97 offset0:8 offset1:41
	v_med3_f32 v24, v10, s69, v94
	ds_read2_b32 v[10:11], v97 offset0:74 offset1:107
	v_med3_f32 v26, v12, s69, v94
	ds_read2_b32 v[12:13], v97 offset0:140 offset1:173
	v_med3_f32 v28, v14, s69, v94
	ds_read2_b32 v[14:15], v97 offset0:206 offset1:239
	ds_read2_b32 v[30:31], v96 offset0:222 offset1:255
	v_mul_f32_e32 v0, 0x43000000, v0
	v_mul_f32_e32 v1, 0x43000000, v1
	s_waitcnt lgkmcnt(6)
	v_mul_f32_e32 v4, 0x43000000, v4
	v_mul_f32_e32 v5, 0x43000000, v5
	s_waitcnt lgkmcnt(5)
	v_mul_f32_e32 v6, 0x43000000, v6
	v_mul_f32_e32 v7, 0x43000000, v7
	s_waitcnt lgkmcnt(4)
	v_mul_f32_e32 v8, 0x43000000, v8
	v_mul_f32_e32 v9, 0x43000000, v9
	s_waitcnt lgkmcnt(3)
	v_mul_f32_e32 v10, 0x43000000, v10
	v_mul_f32_e32 v11, 0x43000000, v11
	s_waitcnt lgkmcnt(2)
	v_mul_f32_e32 v12, 0x43000000, v12
	v_mul_f32_e32 v13, 0x43000000, v13
	v_mul_f32_e32 v29, 0x43000000, v29
	s_waitcnt lgkmcnt(1)
	v_mul_f32_e32 v14, 0x43000000, v14
	s_waitcnt lgkmcnt(0)
	v_mul_f32_e32 v30, 0x43000000, v30
	v_mul_f32_e32 v15, 0x43000000, v15
	v_mul_f32_e32 v31, 0x43000000, v31
	v_med3_f32 v0, v0, s69, v94
	v_med3_f32 v1, v1, s69, v94
	v_med3_f32 v2, v2, s69, v94
	v_med3_f32 v3, v3, s69, v94
	v_med3_f32 v4, v4, s69, v94
	v_med3_f32 v5, v5, s69, v94
	v_med3_f32 v6, v6, s69, v94
	v_med3_f32 v7, v7, s69, v94
	v_med3_f32 v8, v8, s69, v94
	v_med3_f32 v9, v9, s69, v94
	v_med3_f32 v10, v10, s69, v94
	v_med3_f32 v11, v11, s69, v94
	v_med3_f32 v12, v12, s69, v94
	v_med3_f32 v13, v13, s69, v94
	v_med3_f32 v29, v29, s69, v94
	v_med3_f32 v14, v14, s69, v94
	v_med3_f32 v30, v30, s69, v94
	v_med3_f32 v15, v15, s69, v94
	v_med3_f32 v31, v31, s69, v94
	v_cvt_scalef32_2xpk16_fp6_f32 v[0:5], v[0:15], v[16:31], 1.0
	ds_write_b128 v121, v[0:3] offset:8480
	v_mov_b32_e32 v0, v4
	v_mov_b32_e32 v1, v5
	v_mov_b32_e32 v2, v33
	v_mov_b32_e32 v3, v33
	ds_write_b64 v123, v[0:1] offset:8512
	s_waitcnt lgkmcnt(0)
	s_barrier
; #define LAS __attribute__((address_space(3)))
; #define LDS_WAIT() asm volatile("s_waitcnt lgkmcnt(0)" ::: "memory")
;     __device__ __forceinline__ unsigned a(const pg8::Unit& u) const { return (unsigned)u.pm * (256u * K * 2u); }
;     __device__ __forceinline__ unsigned a(const pg8::Unit& u) const { return (unsigned)u.pm * (256u * K * 2u); }
;     __device__ __forceinline__ unsigned a(const pg8::Unit& u) const { return (unsigned)u.pm * (256u * K * 2u); }
;     __device__ __forceinline__ unsigned a(const pg8::Unit& u) const { return (unsigned)u.pm * (256u * K * 2u); }
;     __device__ __forceinline__ unsigned a(const pg8::Unit& u) const { return (unsigned)u.pm * (256u * K * 2u); }
; __device__ __forceinline__ void p0_transpose_pair_fp6(const float* W, int K, int N, int ncol0, unsigned char* WT6, int row0, LAS float* scr, int kb, int lane) {
;     ...
;         const int k0 = 64 * (kb + h);
; #pragma unroll 8
;         for (int i = 0; i < 8; ++i) { const int kk = 8 * i + (lane >> 3), n4 = (lane & 7) * 4;
;         const f32x4 v4 = *(const f32x4*)(W + (size_t)(k0 + kk) * N + ncol0 + n4); LAS float* d4 = scr + kk * 33 + n4; d4[0] = v4[0]; d4[1] = v4[1]; d4[2] = v4[2]; d4[3] = v4[3]; }
;         LDS_WAIT(); asm volatile("" ::: "memory");
;         f32x16v a, b;
; #pragma unroll
;         for (int i = 0; i < 16; ++i) { a[i] = __builtin_amdgcn_fmed3f(scr[(grp * 32 + i) * 33 + n] * W6_SCALE, -7.5f, 7.5f); b[i] = __builtin_amdgcn_fmed3f(scr[(grp * 32 + 16 + i) * 33 + n] * W6_SCALE, -7.5f, 7.5f); }
;     ...
; #pragma unroll
;     for (int j = 0; j < 4; ++j) { const int q = j * 64 + lane;
;         const u32x4 t = *(const LAS u32x4*)(stg + (q >> 3) * 36 + (q & 7) * 4);
;         *(u32x4*)(WT6 + (size_t)(row0 + (q >> 3)) * K + (kb >> 1) * 128 + (q & 7) * 16) = t; }
;     LDS_WAIT(); asm volatile("" ::: "memory");
	ds_read_b128 v[0:3], v124 offset:8448
	v_lshl_add_u64 v[8:9], v[54:55], 0, s[58:59]
	v_lshlrev_b64 v[4:5], 12, v[56:57]
	v_lshl_add_u64 v[10:11], v[8:9], 0, v[4:5]
	v_bfe_u32 v126, v56, 6, 1
	v_bfe_u32 v117, v66, 3, 1
	v_and_b32_e32 v117, v117, v126
	v_mul_u32_u24_e32 v117, 0xfc0, v117
	v_sub_u32_e32 v117, 0, v117
	v_mul_u32_u24_e32 v127, 0x3ffe0, v126
	v_sub_u32_e32 v127, 0, v127
	v_sub_u32_e32 v127, v127, v125
	v_bfe_i32 v116, v66, 2, 1
	v_bfi_b32 v118, v116, v127, v117
	v_ashrrev_i32_e32 v119, 31, v118
	v_lshlrev_b32_e32 v126, 6, v126
	v_sub_u32_e32 v126, 32, v126
	v_add_u32_e32 v126, v127, v126
	v_bfi_b32 v116, v116, v126, v117
	v_ashrrev_i32_e32 v117, 31, v116
	v_lshl_add_u64 v[10:11], v[10:11], 0, v[118:119]
	ds_read_b128 v[4:7], v124 offset:9600
	s_waitcnt lgkmcnt(1)
	global_store_dwordx4 v[10:11], v[0:3], off
	s_mov_b64 s[66:67], 0
	s_nop 0
	v_add_u32_e32 v0, 8, v56
	v_mov_b32_e32 v1, v33
	v_lshlrev_b64 v[0:1], 12, v[0:1]
	v_lshl_add_u64 v[0:1], v[8:9], 0, v[0:1]
	v_lshl_add_u64 v[0:1], v[0:1], 0, v[116:117]
	s_waitcnt lgkmcnt(0)
	global_store_dwordx4 v[0:1], v[4:7], off
	ds_read_b128 v[0:3], v124 offset:10752
	s_nop 0
	v_add_u32_e32 v4, 16, v56
	v_mov_b32_e32 v5, v33
	v_lshlrev_b64 v[4:5], 12, v[4:5]
	v_lshl_add_u64 v[10:11], v[8:9], 0, v[4:5]
	v_lshl_add_u64 v[10:11], v[10:11], 0, v[118:119]
	ds_read_b128 v[4:7], v124 offset:11904
	s_waitcnt lgkmcnt(1)
	global_store_dwordx4 v[10:11], v[0:3], off
	s_nop 1
	v_add_u32_e32 v0, 24, v56
	v_mov_b32_e32 v1, v33
	v_lshlrev_b64 v[0:1], 12, v[0:1]
	v_lshl_add_u64 v[0:1], v[8:9], 0, v[0:1]
	v_lshl_add_u64 v[0:1], v[0:1], 0, v[116:117]
	s_waitcnt lgkmcnt(0)
	global_store_dwordx4 v[0:1], v[4:7], off
	s_waitcnt lgkmcnt(0)
.LBB0_47:
	s_andn2_b64 vcc, exec, s[66:67]
	s_cbranch_vccnz .LBB0_14
	s_ashr_i32 s63, s62, 31
	s_lshl_b64 s[62:63], s[62:63], 2
	s_add_u32 s62, s16, s62
	s_addc_u32 s63, s17, s63
	v_lshl_add_u64 v[0:1], s[62:63], 0, v[32:33]
	v_lshl_add_u64 v[62:63], v[0:1], 0, s[8:9]
	v_lshl_add_u64 v[0:1], v[62:63], 0, v[60:61]
	v_lshl_add_u64 v[4:5], v[62:63], 0, v[58:59]
	v_mad_i64_i32 v[8:9], s[62:63], v104, s68, v[62:63]
	v_mad_i64_i32 v[12:13], s[62:63], v103, s68, v[62:63]
	v_mad_i64_i32 v[16:17], s[62:63], v102, s68, v[62:63]
	v_mad_i64_i32 v[20:21], s[62:63], v101, s68, v[62:63]
	v_mad_i64_i32 v[24:25], s[62:63], v100, s68, v[62:63]
	global_load_dwordx4 v[0:3], v[0:1], off
	s_nop 0
	global_load_dwordx4 v[4:7], v[4:5], off
	s_nop 0
	global_load_dwordx4 v[8:11], v[8:9], off
	s_nop 0
	global_load_dwordx4 v[12:15], v[12:13], off
	s_nop 0
	global_load_dwordx4 v[16:19], v[16:17], off
	s_nop 0
	global_load_dwordx4 v[20:23], v[20:21], off
	s_nop 0
	global_load_dwordx4 v[24:27], v[24:25], off
	v_mad_i64_i32 v[28:29], s[62:63], v99, s68, v[62:63]
	global_load_dwordx4 v[28:31], v[28:29], off
	v_mov_b32_e32 v32, v33
	s_or_b32 s0, s58, 64
	s_ashr_i32 s59, s58, 31
	v_ashrrev_i32_e32 v57, 31, v56
	s_waitcnt vmcnt(7)
	ds_write2_b32 v37, v0, v1 offset1:1
	ds_write2_b32 v37, v2, v3 offset0:2 offset1:3
	s_waitcnt vmcnt(6)
	ds_write2_b32 v79, v4, v5 offset1:1
	ds_write2_b32 v80, v6, v7 offset1:1
	s_waitcnt vmcnt(5)
	ds_write2_b32 v81, v8, v9 offset1:1
	ds_write2_b32 v82, v10, v11 offset1:1
	s_waitcnt vmcnt(4)
	ds_write2_b32 v83, v12, v13 offset1:1
	ds_write2_b32 v84, v14, v15 offset1:1
	s_waitcnt vmcnt(3)
	ds_write2_b32 v85, v16, v17 offset1:1
	ds_write2_b32 v86, v18, v19 offset1:1
	s_waitcnt vmcnt(2)
	ds_write2_b32 v87, v20, v21 offset1:1
	ds_write2_b32 v88, v22, v23 offset1:1
	s_waitcnt vmcnt(1)
	ds_write2_b32 v89, v24, v25 offset1:1
	ds_write2_b32 v90, v26, v27 offset1:1
	s_waitcnt vmcnt(0)
	ds_write2_b32 v91, v28, v29 offset1:1
	ds_write2_b32 v92, v30, v31 offset1:1
	s_waitcnt lgkmcnt(0)
	ds_read2_b32 v[0:1], v75 offset1:33
	ds_read2_b32 v[2:3], v98 offset0:16 offset1:49
	ds_read2_b32 v[4:5], v75 offset0:66 offset1:99
	ds_read2_b32 v[6:7], v98 offset0:82 offset1:115
	ds_read2_b32 v[8:9], v75 offset0:132 offset1:165
	ds_read2_b32 v[10:11], v98 offset0:148 offset1:181
	ds_read2_b32 v[12:13], v75 offset0:198 offset1:231
	ds_read2_b32 v[14:15], v98 offset0:214 offset1:247
	ds_read2_b32 v[16:17], v97 offset0:8 offset1:41
	ds_read2_b32 v[18:19], v96 offset0:24 offset1:57
	ds_read2_b32 v[26:27], v97 offset0:74 offset1:107
	ds_read2_b32 v[28:29], v96 offset0:90 offset1:123
	s_waitcnt lgkmcnt(4)
	v_mul_f32_e32 v14, 0x43000000, v14
	v_mul_f32_e32 v15, 0x43000000, v15
	v_med3_f32 v22, v14, s69, v94
	v_med3_f32 v23, v15, s69, v94
	ds_read2_b32 v[14:15], v96 offset0:156 offset1:189
	v_mul_f32_e32 v2, 0x43000000, v2
	v_mul_f32_e32 v3, 0x43000000, v3
	v_mul_f32_e32 v4, 0x43000000, v4
	v_mul_f32_e32 v6, 0x43000000, v6
	v_mul_f32_e32 v5, 0x43000000, v5
	v_mul_f32_e32 v7, 0x43000000, v7
	v_mul_f32_e32 v8, 0x43000000, v8
	v_mul_f32_e32 v9, 0x43000000, v9
	v_mul_f32_e32 v12, 0x43000000, v12
	v_mul_f32_e32 v13, 0x43000000, v13
	s_waitcnt lgkmcnt(4)
	v_mul_f32_e32 v24, 0x43000000, v16
	s_waitcnt lgkmcnt(3)
	v_mul_f32_e32 v25, 0x43000000, v18
	v_mul_f32_e32 v30, 0x43000000, v17
	v_mul_f32_e32 v31, 0x43000000, v19
	ds_read2_b32 v[58:59], v96 offset0:222 offset1:255
	v_med3_f32 v16, v2, s69, v94
	v_med3_f32 v17, v3, s69, v94
	v_med3_f32 v2, v4, s69, v94
	v_med3_f32 v18, v6, s69, v94
	v_med3_f32 v3, v5, s69, v94
	v_med3_f32 v19, v7, s69, v94
	v_med3_f32 v4, v8, s69, v94
	v_med3_f32 v5, v9, s69, v94
	v_med3_f32 v6, v12, s69, v94
	v_med3_f32 v7, v13, s69, v94
	v_med3_f32 v8, v24, s69, v94
	v_med3_f32 v24, v25, s69, v94
	v_med3_f32 v9, v30, s69, v94
	v_med3_f32 v25, v31, s69, v94
	ds_read2_b32 v[12:13], v97 offset0:140 offset1:173
	ds_read2_b32 v[30:31], v97 offset0:206 offset1:239
	v_mul_f32_e32 v11, 0x43000000, v11
	s_waitcnt lgkmcnt(3)
; #define LAS __attribute__((address_space(3)))
; #define LDS_WAIT() asm volatile("s_waitcnt lgkmcnt(0)" ::: "memory")
;     __device__ __forceinline__ unsigned a(const pg8::Unit& u) const { return (unsigned)u.pm * (256u * K * 2u); }
;     __device__ __forceinline__ unsigned a(const pg8::Unit& u) const { return (unsigned)u.pm * (256u * K * 2u); }
;     __device__ __forceinline__ unsigned a(const pg8::Unit& u) const { return (unsigned)u.pm * (256u * K * 2u); }
;     __device__ __forceinline__ unsigned a(const pg8::Unit& u) const { return (unsigned)u.pm * (256u * K * 2u); }
;     __device__ __forceinline__ unsigned a(const pg8::Unit& u) const { return (unsigned)u.pm * (256u * K * 2u); }
; __device__ __forceinline__ void p0_transpose_pair_fp6(const float* W, int K, int N, int ncol0, unsigned char* WT6, int row0, LAS float* scr, int kb, int lane) {
;     ...
;         for (int i = 0; i < 8; ++i) { const int kk = 8 * i + (lane >> 3), n4 = (lane & 7) * 4;
;         const f32x4 v4 = *(const f32x4*)(W + (size_t)(k0 + kk) * N + ncol0 + n4); LAS float* d4 = scr + kk * 33 + n4; d4[0] = v4[0]; d4[1] = v4[1]; d4[2] = v4[2]; d4[3] = v4[3]; }
;         LDS_WAIT(); asm volatile("" ::: "memory");
;         f32x16v a, b;
; #pragma unroll
;         for (int i = 0; i < 16; ++i) { a[i] = __builtin_amdgcn_fmed3f(scr[(grp * 32 + i) * 33 + n] * W6_SCALE, -7.5f, 7.5f); b[i] = __builtin_amdgcn_fmed3f(scr[(grp * 32 + 16 + i) * 33 + n] * W6_SCALE, -7.5f, 7.5f); }
;         const u32x6v p = __builtin_amdgcn_cvt_scalef32_2xpk16_fp6_f32(a, b, 1.0f);
;         const int fq = h * 2 + grp;
;         *(LAS u32x4*)(stg + n * 36 + fq * 4) = (u32x4){p[0], p[1], p[2], p[3]};
;         *(LAS u32x4*)(stg + n * 36 + 16 + fq * 4) = (u32x4){p[4], p[5], 0u, 0u};
;         LDS_WAIT(); asm volatile("" ::: "memory");
	v_mul_f32_e32 v14, 0x43000000, v14
	v_mul_f32_e32 v10, 0x43000000, v10
	v_med3_f32 v21, v11, s69, v94
	v_mul_f32_e32 v11, 0x43000000, v28
	v_med3_f32 v28, v14, s69, v94
	v_mul_f32_e32 v14, 0x43000000, v15
	s_waitcnt lgkmcnt(2)
	v_mul_f32_e32 v15, 0x43000000, v58
	v_mul_f32_e32 v0, 0x43000000, v0
	v_mul_f32_e32 v1, 0x43000000, v1
	v_med3_f32 v20, v10, s69, v94
	v_mul_f32_e32 v10, 0x43000000, v26
	v_med3_f32 v26, v11, s69, v94
	v_mul_f32_e32 v11, 0x43000000, v27
	v_mul_f32_e32 v27, 0x43000000, v29
	s_waitcnt lgkmcnt(1)
	v_mul_f32_e32 v12, 0x43000000, v12
	v_mul_f32_e32 v13, 0x43000000, v13
	v_med3_f32 v29, v14, s69, v94
	s_waitcnt lgkmcnt(0)
	v_mul_f32_e32 v14, 0x43000000, v30
	v_med3_f32 v30, v15, s69, v94
	v_mul_f32_e32 v15, 0x43000000, v31
	v_mul_f32_e32 v31, 0x43000000, v59
	v_med3_f32 v0, v0, s69, v94
	v_med3_f32 v1, v1, s69, v94
	v_med3_f32 v10, v10, s69, v94
	v_med3_f32 v11, v11, s69, v94
	v_med3_f32 v27, v27, s69, v94
	v_med3_f32 v12, v12, s69, v94
	v_med3_f32 v13, v13, s69, v94
	v_med3_f32 v14, v14, s69, v94
	v_med3_f32 v15, v15, s69, v94
	v_med3_f32 v31, v31, s69, v94
	v_cvt_scalef32_2xpk16_fp6_f32 v[0:5], v[0:15], v[16:31], 1.0
	v_mov_b32_e32 v30, v4
	v_mov_b32_e32 v31, v5
	ds_write_b128 v120, v[0:3] offset:8448
	ds_write_b64 v122, v[30:31] offset:8512
	s_waitcnt lgkmcnt(0)
	v_or_b32_e32 v0, s0, v64
	v_or_b32_e32 v4, s0, v65
	v_or_b32_e32 v6, s0, v67
	v_or_b32_e32 v7, s0, v69
	v_or_b32_e32 v10, s0, v70
	v_or_b32_e32 v14, s0, v71
	v_or_b32_e32 v22, s0, v72
	v_mad_i64_i32 v[0:1], s[62:63], v0, s68, v[62:63]
	v_mad_i64_i32 v[4:5], s[62:63], v4, s68, v[62:63]
	v_mad_i64_i32 v[8:9], s[62:63], v6, s68, v[62:63]
	v_mad_i64_i32 v[12:13], s[62:63], v7, s68, v[62:63]
	v_mad_i64_i32 v[16:17], s[62:63], v10, s68, v[62:63]
	v_mad_i64_i32 v[20:21], s[62:63], v14, s68, v[62:63]
	v_mad_i64_i32 v[24:25], s[62:63], v22, s68, v[62:63]
	global_load_dwordx4 v[0:3], v[0:1], off
	s_nop 0
	global_load_dwordx4 v[4:7], v[4:5], off
	s_nop 0
	global_load_dwordx4 v[8:11], v[8:9], off
	s_nop 0
	global_load_dwordx4 v[12:15], v[12:13], off
	s_nop 0
	global_load_dwordx4 v[16:19], v[16:17], off
	s_nop 0
	global_load_dwordx4 v[20:23], v[20:21], off
	s_nop 0
	global_load_dwordx4 v[24:27], v[24:25], off
	v_or_b32_e32 v28, s0, v73
	v_mad_i64_i32 v[28:29], s[62:63], v28, s68, v[62:63]
	global_load_dwordx4 v[28:31], v[28:29], off
	s_waitcnt vmcnt(7)
	ds_write2_b32 v37, v0, v1 offset1:1
	ds_write2_b32 v37, v2, v3 offset0:2 offset1:3
	s_waitcnt vmcnt(6)
	ds_write2_b32 v79, v4, v5 offset1:1
	ds_write2_b32 v80, v6, v7 offset1:1
	s_waitcnt vmcnt(5)
	ds_write2_b32 v81, v8, v9 offset1:1
	ds_write2_b32 v82, v10, v11 offset1:1
	s_waitcnt vmcnt(4)
	ds_write2_b32 v83, v12, v13 offset1:1
	ds_write2_b32 v84, v14, v15 offset1:1
	s_waitcnt vmcnt(3)
	ds_write2_b32 v85, v16, v17 offset1:1
	ds_write2_b32 v86, v18, v19 offset1:1
	s_waitcnt vmcnt(2)
	ds_write2_b32 v87, v20, v21 offset1:1
	ds_write2_b32 v88, v22, v23 offset1:1
	s_waitcnt vmcnt(1)
	ds_write2_b32 v89, v24, v25 offset1:1
	ds_write2_b32 v90, v26, v27 offset1:1
	s_waitcnt vmcnt(0)
	ds_write2_b32 v91, v28, v29 offset1:1
	ds_write2_b32 v92, v30, v31 offset1:1
	s_waitcnt lgkmcnt(0)
	ds_read2_b32 v[0:1], v75 offset1:33
	ds_read2_b32 v[2:3], v98 offset0:16 offset1:49
	ds_read2_b32 v[6:7], v98 offset0:82 offset1:115
	ds_read2_b32 v[8:9], v98 offset0:148 offset1:181
	ds_read2_b32 v[10:11], v98 offset0:214 offset1:247
	ds_read2_b32 v[12:13], v96 offset0:24 offset1:57
	s_waitcnt lgkmcnt(4)
	v_mul_f32_e32 v3, 0x43000000, v3
	ds_read2_b32 v[14:15], v96 offset0:90 offset1:123
	v_med3_f32 v17, v3, s69, v94
	s_waitcnt lgkmcnt(4)
	v_mul_f32_e32 v3, 0x43000000, v6
	v_mul_f32_e32 v6, 0x43000000, v7
	ds_read2_b32 v[28:29], v96 offset0:156 offset1:189
	ds_read2_b32 v[4:5], v75 offset0:66 offset1:99
	v_med3_f32 v19, v6, s69, v94
	s_waitcnt lgkmcnt(5)
	v_mul_f32_e32 v6, 0x43000000, v8
	v_mul_f32_e32 v8, 0x43000000, v9
	v_med3_f32 v21, v8, s69, v94
	s_waitcnt lgkmcnt(4)
	v_mul_f32_e32 v8, 0x43000000, v10
	v_mul_f32_e32 v10, 0x43000000, v11
	v_med3_f32 v23, v10, s69, v94
	s_waitcnt lgkmcnt(3)
	v_mul_f32_e32 v10, 0x43000000, v12
	v_mul_f32_e32 v12, 0x43000000, v13
	v_med3_f32 v25, v12, s69, v94
	s_waitcnt lgkmcnt(2)
	v_mul_f32_e32 v12, 0x43000000, v14
	v_mul_f32_e32 v14, 0x43000000, v15
	v_mul_f32_e32 v2, 0x43000000, v2
	v_med3_f32 v27, v14, s69, v94
	s_waitcnt lgkmcnt(1)
	v_mul_f32_e32 v14, 0x43000000, v28
	v_med3_f32 v16, v2, s69, v94
	s_waitcnt lgkmcnt(0)
	v_mul_f32_e32 v2, 0x43000000, v4
	v_med3_f32 v18, v3, s69, v94
	v_mul_f32_e32 v3, 0x43000000, v5
	ds_read2_b32 v[4:5], v75 offset0:132 offset1:165
	v_med3_f32 v20, v6, s69, v94
	ds_read2_b32 v[6:7], v75 offset0:198 offset1:231
	v_med3_f32 v22, v8, s69, v94
	ds_read2_b32 v[8:9], v97 offset0:8 offset1:41
	v_med3_f32 v24, v10, s69, v94
	ds_read2_b32 v[10:11], v97 offset0:74 offset1:107
	v_med3_f32 v26, v12, s69, v94
	ds_read2_b32 v[12:13], v97 offset0:140 offset1:173
	v_med3_f32 v28, v14, s69, v94
	ds_read2_b32 v[14:15], v97 offset0:206 offset1:239
	ds_read2_b32 v[30:31], v96 offset0:222 offset1:255
	v_mul_f32_e32 v0, 0x43000000, v0
	v_mul_f32_e32 v1, 0x43000000, v1
	s_waitcnt lgkmcnt(6)
	v_mul_f32_e32 v4, 0x43000000, v4
	v_mul_f32_e32 v5, 0x43000000, v5
	s_waitcnt lgkmcnt(5)
	v_mul_f32_e32 v6, 0x43000000, v6
	v_mul_f32_e32 v7, 0x43000000, v7
	s_waitcnt lgkmcnt(4)
	v_mul_f32_e32 v8, 0x43000000, v8
	v_mul_f32_e32 v9, 0x43000000, v9
	s_waitcnt lgkmcnt(3)
	v_mul_f32_e32 v10, 0x43000000, v10
	v_mul_f32_e32 v11, 0x43000000, v11
	s_waitcnt lgkmcnt(2)
	v_mul_f32_e32 v12, 0x43000000, v12
	v_mul_f32_e32 v13, 0x43000000, v13
	v_mul_f32_e32 v29, 0x43000000, v29
	s_waitcnt lgkmcnt(1)
	v_mul_f32_e32 v14, 0x43000000, v14
	s_waitcnt lgkmcnt(0)
	v_mul_f32_e32 v30, 0x43000000, v30
	v_mul_f32_e32 v15, 0x43000000, v15
	v_mul_f32_e32 v31, 0x43000000, v31
	v_med3_f32 v0, v0, s69, v94
	v_med3_f32 v1, v1, s69, v94
	v_med3_f32 v2, v2, s69, v94
	v_med3_f32 v3, v3, s69, v94
	v_med3_f32 v4, v4, s69, v94
	v_med3_f32 v5, v5, s69, v94
	v_med3_f32 v6, v6, s69, v94
	v_med3_f32 v7, v7, s69, v94
	v_med3_f32 v8, v8, s69, v94
	v_med3_f32 v9, v9, s69, v94
	v_med3_f32 v10, v10, s69, v94
	v_med3_f32 v11, v11, s69, v94
	v_med3_f32 v12, v12, s69, v94
	v_med3_f32 v13, v13, s69, v94
	v_med3_f32 v29, v29, s69, v94
	v_med3_f32 v14, v14, s69, v94
	v_med3_f32 v30, v30, s69, v94
	v_med3_f32 v15, v15, s69, v94
	v_med3_f32 v31, v31, s69, v94
	v_cvt_scalef32_2xpk16_fp6_f32 v[0:5], v[0:15], v[16:31], 1.0
	v_mov_b32_e32 v30, v4
	v_mov_b32_e32 v31, v5
	ds_write_b128 v121, v[0:3] offset:8480
	ds_write_b64 v123, v[30:31] offset:8512
	s_waitcnt lgkmcnt(0)
	s_barrier
; #define LAS __attribute__((address_space(3)))
; #define LDS_WAIT() asm volatile("s_waitcnt lgkmcnt(0)" ::: "memory")
; __device__ __forceinline__ void p0_transpose_pair_fp6(const float* W, int K, int N, int ncol0, unsigned char* WT6, int row0, LAS float* scr, int kb, int lane) {
;     ...
; #pragma unroll
;     for (int j = 0; j < 4; ++j) { const int q = j * 64 + lane;
;         const u32x4 t = *(const LAS u32x4*)(stg + (q >> 3) * 36 + (q & 7) * 4);
;         *(u32x4*)(WT6 + (size_t)(row0 + (q >> 3)) * K + (kb >> 1) * 128 + (q & 7) * 16) = t; }
;     LDS_WAIT(); asm volatile("" ::: "memory");
	ds_read_b128 v[0:3], v124 offset:8448
	v_lshl_add_u64 v[8:9], v[54:55], 0, s[58:59]
	v_lshlrev_b64 v[4:5], 12, v[56:57]
	v_lshl_add_u64 v[10:11], v[8:9], 0, v[4:5]
	v_bfe_u32 v126, v56, 6, 1
	v_bfe_u32 v117, v66, 3, 1
	v_and_b32_e32 v117, v117, v126
	v_mul_u32_u24_e32 v117, 0xfc0, v117
	v_sub_u32_e32 v117, 0, v117
	v_mul_u32_u24_e32 v127, 0x3ffe0, v126
	v_sub_u32_e32 v127, 0, v127
	v_sub_u32_e32 v127, v127, v125
	v_bfe_i32 v116, v66, 2, 1
	v_bfi_b32 v118, v116, v127, v117
	v_ashrrev_i32_e32 v119, 31, v118
	v_lshlrev_b32_e32 v126, 6, v126
	v_sub_u32_e32 v126, 32, v126
	v_add_u32_e32 v126, v127, v126
	v_bfi_b32 v116, v116, v126, v117
	v_ashrrev_i32_e32 v117, 31, v116
	v_lshl_add_u64 v[10:11], v[10:11], 0, v[118:119]
	ds_read_b128 v[4:7], v124 offset:9600
	s_waitcnt lgkmcnt(1)
	global_store_dwordx4 v[10:11], v[0:3], off
	s_nop 1
	v_add_u32_e32 v0, 8, v56
	v_ashrrev_i32_e32 v1, 31, v0
	v_lshlrev_b64 v[0:1], 12, v[0:1]
	v_lshl_add_u64 v[0:1], v[8:9], 0, v[0:1]
	v_lshl_add_u64 v[0:1], v[0:1], 0, v[116:117]
	s_waitcnt lgkmcnt(0)
	global_store_dwordx4 v[0:1], v[4:7], off
	ds_read_b128 v[0:3], v124 offset:10752
	s_nop 0
	v_add_u32_e32 v4, 16, v56
	v_ashrrev_i32_e32 v5, 31, v4
	v_lshlrev_b64 v[4:5], 12, v[4:5]
	v_lshl_add_u64 v[10:11], v[8:9], 0, v[4:5]
	v_lshl_add_u64 v[10:11], v[10:11], 0, v[118:119]
	ds_read_b128 v[4:7], v124 offset:11904
	s_waitcnt lgkmcnt(1)
	global_store_dwordx4 v[10:11], v[0:3], off
	s_nop 1
	v_add_u32_e32 v0, 24, v56
	v_ashrrev_i32_e32 v1, 31, v0
	v_lshlrev_b64 v[0:1], 12, v[0:1]
	v_lshl_add_u64 v[0:1], v[8:9], 0, v[0:1]
	v_lshl_add_u64 v[0:1], v[0:1], 0, v[116:117]
	s_waitcnt lgkmcnt(0)
	global_store_dwordx4 v[0:1], v[4:7], off
	s_waitcnt lgkmcnt(0)
	s_branch .LBB0_14
